# P7a T-block column chains: MFMA accumulators feed the next product directly (k-permuted operands), no LDS round trip for W and T
# speedup vs baseline: 1.0010x; 1.0005x over previous
; #define BAR_LDS() do { asm volatile("s_waitcnt lgkmcnt(0)" ::: "memory"); __builtin_amdgcn_s_barrier(); asm volatile("" ::: "memory"); } while (0)
; __device__ __forceinline__ unsigned pk2(float lo, float hi) { const f32x2c v = {lo, hi}; const bf16x2c b = __builtin_convertvector(v, bf16x2c); return __builtin_bit_cast(unsigned, b); }
; #define TDW(r_, wp) ({ const LAS float* tr_ = TD + (r_) * 256 + i * 16; const LAS float* bp_ = (wp) + j; float a_ = 0.f; \
;         _Pragma("unroll") for (int u4 = 0; u4 < 4; ++u4) { const f32x4 t4 = *(const LAS f32x4*)(tr_ + 4 * u4); \
;             a_ += (t4.x * bp_[(4 * u4) * 16] + t4.y * bp_[(4 * u4 + 1) * 16]) + (t4.z * bp_[(4 * u4 + 2) * 16] + t4.w * bp_[(4 * u4 + 3) * 16]); } a_; })
; __device__ __forceinline__ void chunk_pre(const Params& p, LAS unsigned char* lds, int item, int next_item, int tid, int wave, int lane, h16 (&raw)[48]) {
;     ...
;     for (int e = tid; e < 3 * 256; e += 512) { const int bk = e >> 8, i = (e >> 4) & 15, j = e & 15; Wf[bk * 256 + i * 16 + j] = M16(bk + 1, bk, TD + bk * 256); }
;     BAR_LDS();
;     for (int e = tid; e < 3 * 256; e += 512) { const int bk = e >> 8, i = (e >> 4) & 15, j = e & 15; const float t = TDW(bk + 1, Wf + bk * 256);
;         Toff[bk * 256 + i * 16 + j] = t; Tb[(16 * (bk + 1) + i) * MS + 16 * bk + j] = (bf16_t)(pk2(t, 0.f) & 0xffffu); }
;     BAR_LDS();
;     { const int bk = tid >> 8, i = (tid >> 4) & 15, j = tid & 15; Wf[bk * 256 + i * 16 + j] = M16(bk + 2, bk, TD + bk * 256) + M16(bk + 2, bk + 1, Toff + bk * 256); }
;     BAR_LDS();
;     { const int bk = tid >> 8, i = (tid >> 4) & 15, j = tid & 15; const float t = TDW(bk + 2, Wf + bk * 256);
;       Toff[(3 + bk) * 256 + i * 16 + j] = t; Tb[(16 * (bk + 2) + i) * MS + 16 * bk + j] = (bf16_t)(pk2(t, 0.f) & 0xffffu); }
;     BAR_LDS();
;     if (tid < 256) { const int i = tid >> 4, j = tid & 15; Wf[i * 16 + j] = M16(3, 0, TD) + M16(3, 1, Toff) + M16(3, 2, Toff + 3 * 256); }
;     BAR_LDS();
;     if (tid < 256) { const int i = tid >> 4, j = tid & 15; const float t = TDW(3, Wf); Tb[(48 + i) * MS + j] = (bf16_t)(pk2(t, 0.f) & 0xffffu); }
;     BAR_LDS();
.LBB0_935:
	s_or_b64 exec, exec, s[12:13]
	s_waitcnt lgkmcnt(0)
	s_barrier
	v_readlane_b32 s100, v244, 14
	v_mbcnt_lo_u32_b32 v9, -1, 0
	v_mbcnt_hi_u32_b32 v9, -1, v9
	s_nop 1
	s_cmp_gt_u32 s100, 2
	s_cbranch_scc1 .Llev_done
	v_and_b32_e32 v10, 15, v9
	v_lshrrev_b32_e32 v11, 4, v9
	v_lshlrev_b32_e32 v12, 4, v11
	v_lshlrev_b32_e32 v13, 2, v10
	v_lshl_add_u32 v4, v10, 8, v12
	v_add_u32_e32 v4, 0x16800, v4
	v_lshl_add_u32 v5, v10, 6, v12
	v_add_u32_e32 v5, 0x1f000, v5
	v_lshl_add_u32 v7, v11, 8, v13
	v_add_u32_e32 v7, 0x1f000, v7
	v_lshlrev_b32_e32 v14, 1, v10
	v_mov_b32_e32 v15, 0x240
	v_mad_u32_u24 v8, v11, v15, v14
	s_cmp_eq_u32 s100, 1
	s_cbranch_scc1 .Llev_col1
	s_cmp_eq_u32 s100, 2
	s_cbranch_scc1 .Llev_col2
	ds_read_b32 v10, v7 offset:0
	ds_read_b32 v11, v7 offset:64
	ds_read_b32 v12, v7 offset:128
	ds_read_b32 v13, v7 offset:192
	ds_read_b128 v[188:191], v4 offset:4096
	ds_read_b128 v[192:195], v5 offset:1024
	ds_read_b128 v[196:199], v4 offset:8192
	ds_read_b128 v[200:203], v4 offset:8256
	ds_read_b128 v[220:223], v5 offset:2048
	ds_read_b128 v[224:227], v4 offset:12288
	ds_read_b128 v[228:231], v4 offset:12352
	ds_read_b128 v[232:235], v4 offset:12416
	ds_read_b128 v[236:239], v5 offset:3072
	s_waitcnt lgkmcnt(8)
	v_mfma_f32_16x16x4_f32 v[36:39], v188, v10, 0
	v_mfma_f32_16x16x4_f32 v[36:39], v189, v11, v[36:39]
	v_mfma_f32_16x16x4_f32 v[36:39], v190, v12, v[36:39]
	v_mfma_f32_16x16x4_f32 v[36:39], v191, v13, v[36:39]
	s_nop 7
	s_nop 1
	s_waitcnt lgkmcnt(7)
	v_mfma_f32_16x16x4_f32 v[14:17], v192, v36, 0
	v_mfma_f32_16x16x4_f32 v[14:17], v193, v37, v[14:17]
	v_mfma_f32_16x16x4_f32 v[14:17], v194, v38, v[14:17]
	v_mfma_f32_16x16x4_f32 v[14:17], v195, v39, v[14:17]
	s_waitcnt lgkmcnt(6)
	v_mfma_f32_16x16x4_f32 v[240:243], v196, v10, 0
	v_mfma_f32_16x16x4_f32 v[240:243], v197, v11, v[240:243]
	v_mfma_f32_16x16x4_f32 v[240:243], v198, v12, v[240:243]
	v_mfma_f32_16x16x4_f32 v[240:243], v199, v13, v[240:243]
	s_nop 5
	s_waitcnt lgkmcnt(5)
	v_mfma_f32_16x16x4_f32 v[240:243], v200, v14, v[240:243]
	v_mfma_f32_16x16x4_f32 v[240:243], v201, v15, v[240:243]
	v_mfma_f32_16x16x4_f32 v[240:243], v202, v16, v[240:243]
	v_mfma_f32_16x16x4_f32 v[240:243], v203, v17, v[240:243]
	v_cvt_pk_bf16_f32 v9, v14, v14
	ds_write_b16 v8, v9 offset:2304
	v_cvt_pk_bf16_f32 v9, v15, v15
	ds_write_b16 v8, v9 offset:2448
	v_cvt_pk_bf16_f32 v9, v16, v16
	ds_write_b16 v8, v9 offset:2592
	v_cvt_pk_bf16_f32 v9, v17, v17
	ds_write_b16 v8, v9 offset:2736
	s_nop 1
	s_waitcnt lgkmcnt(8)
	v_mfma_f32_16x16x4_f32 v[164:167], v220, v240, 0
	v_mfma_f32_16x16x4_f32 v[164:167], v221, v241, v[164:167]
	v_mfma_f32_16x16x4_f32 v[164:167], v222, v242, v[164:167]
	v_mfma_f32_16x16x4_f32 v[164:167], v223, v243, v[164:167]
	s_waitcnt lgkmcnt(7)
	v_mfma_f32_16x16x4_f32 v[36:39], v224, v10, 0
	v_mfma_f32_16x16x4_f32 v[36:39], v225, v11, v[36:39]
	v_mfma_f32_16x16x4_f32 v[36:39], v226, v12, v[36:39]
	v_mfma_f32_16x16x4_f32 v[36:39], v227, v13, v[36:39]
	s_waitcnt lgkmcnt(6)
	v_mfma_f32_16x16x4_f32 v[36:39], v228, v14, v[36:39]
	v_mfma_f32_16x16x4_f32 v[36:39], v229, v15, v[36:39]
	v_mfma_f32_16x16x4_f32 v[36:39], v230, v16, v[36:39]
	v_mfma_f32_16x16x4_f32 v[36:39], v231, v17, v[36:39]
	s_nop 1
	s_waitcnt lgkmcnt(5)
	v_mfma_f32_16x16x4_f32 v[36:39], v232, v164, v[36:39]
	v_mfma_f32_16x16x4_f32 v[36:39], v233, v165, v[36:39]
	v_mfma_f32_16x16x4_f32 v[36:39], v234, v166, v[36:39]
	v_mfma_f32_16x16x4_f32 v[36:39], v235, v167, v[36:39]
	v_cvt_pk_bf16_f32 v9, v164, v164
	ds_write_b16 v8, v9 offset:4608
	v_cvt_pk_bf16_f32 v9, v165, v165
	ds_write_b16 v8, v9 offset:4752
	v_cvt_pk_bf16_f32 v9, v166, v166
	ds_write_b16 v8, v9 offset:4896
	v_cvt_pk_bf16_f32 v9, v167, v167
	ds_write_b16 v8, v9 offset:5040
	s_nop 1
	s_waitcnt lgkmcnt(8)
	v_mfma_f32_16x16x4_f32 v[184:187], v236, v36, 0
	v_mfma_f32_16x16x4_f32 v[184:187], v237, v37, v[184:187]
	v_mfma_f32_16x16x4_f32 v[184:187], v238, v38, v[184:187]
	v_mfma_f32_16x16x4_f32 v[184:187], v239, v39, v[184:187]
	s_nop 7
	s_nop 1
	v_cvt_pk_bf16_f32 v9, v184, v184
	ds_write_b16 v8, v9 offset:6912
	v_cvt_pk_bf16_f32 v9, v185, v185
	ds_write_b16 v8, v9 offset:7056
	v_cvt_pk_bf16_f32 v9, v186, v186
	ds_write_b16 v8, v9 offset:7200
	v_cvt_pk_bf16_f32 v9, v187, v187
	ds_write_b16 v8, v9 offset:7344
	s_branch .Llev_done
; #define BAR_LDS() do { asm volatile("s_waitcnt lgkmcnt(0)" ::: "memory"); __builtin_amdgcn_s_barrier(); asm volatile("" ::: "memory"); } while (0)
; __device__ __forceinline__ unsigned pk2(float lo, float hi) { const f32x2c v = {lo, hi}; const bf16x2c b = __builtin_convertvector(v, bf16x2c); return __builtin_bit_cast(unsigned, b); }
; #define TDW(r_, wp) ({ const LAS float* tr_ = TD + (r_) * 256 + i * 16; const LAS float* bp_ = (wp) + j; float a_ = 0.f; \
;         _Pragma("unroll") for (int u4 = 0; u4 < 4; ++u4) { const f32x4 t4 = *(const LAS f32x4*)(tr_ + 4 * u4); \
;             a_ += (t4.x * bp_[(4 * u4) * 16] + t4.y * bp_[(4 * u4 + 1) * 16]) + (t4.z * bp_[(4 * u4 + 2) * 16] + t4.w * bp_[(4 * u4 + 3) * 16]); } a_; })
; __device__ __forceinline__ void chunk_pre(const Params& p, LAS unsigned char* lds, int item, int next_item, int tid, int wave, int lane, h16 (&raw)[48]) {
;     ...
;     for (int e = tid; e < 3 * 256; e += 512) { const int bk = e >> 8, i = (e >> 4) & 15, j = e & 15; Wf[bk * 256 + i * 16 + j] = M16(bk + 1, bk, TD + bk * 256); }
;     BAR_LDS();
;     for (int e = tid; e < 3 * 256; e += 512) { const int bk = e >> 8, i = (e >> 4) & 15, j = e & 15; const float t = TDW(bk + 1, Wf + bk * 256);
;         Toff[bk * 256 + i * 16 + j] = t; Tb[(16 * (bk + 1) + i) * MS + 16 * bk + j] = (bf16_t)(pk2(t, 0.f) & 0xffffu); }
;     BAR_LDS();
;     { const int bk = tid >> 8, i = (tid >> 4) & 15, j = tid & 15; Wf[bk * 256 + i * 16 + j] = M16(bk + 2, bk, TD + bk * 256) + M16(bk + 2, bk + 1, Toff + bk * 256); }
;     BAR_LDS();
;     { const int bk = tid >> 8, i = (tid >> 4) & 15, j = tid & 15; const float t = TDW(bk + 2, Wf + bk * 256);
;       Toff[(3 + bk) * 256 + i * 16 + j] = t; Tb[(16 * (bk + 2) + i) * MS + 16 * bk + j] = (bf16_t)(pk2(t, 0.f) & 0xffffu); }
;     BAR_LDS();
;     if (tid < 256) { const int i = tid >> 4, j = tid & 15; Wf[i * 16 + j] = M16(3, 0, TD) + M16(3, 1, Toff) + M16(3, 2, Toff + 3 * 256); }
;     BAR_LDS();
;     if (tid < 256) { const int i = tid >> 4, j = tid & 15; const float t = TDW(3, Wf); Tb[(48 + i) * MS + j] = (bf16_t)(pk2(t, 0.f) & 0xffffu); }
;     BAR_LDS();
.Llev_col1:
	ds_read_b32 v10, v7 offset:1024
	ds_read_b32 v11, v7 offset:1088
	ds_read_b32 v12, v7 offset:1152
	ds_read_b32 v13, v7 offset:1216
	ds_read_b128 v[188:191], v4 offset:8256
	ds_read_b128 v[192:195], v5 offset:2048
	ds_read_b128 v[196:199], v4 offset:12352
	ds_read_b128 v[200:203], v4 offset:12416
	ds_read_b128 v[220:223], v5 offset:3072
	s_waitcnt lgkmcnt(4)
	v_mfma_f32_16x16x4_f32 v[36:39], v188, v10, 0
	v_mfma_f32_16x16x4_f32 v[36:39], v189, v11, v[36:39]
	v_mfma_f32_16x16x4_f32 v[36:39], v190, v12, v[36:39]
	v_mfma_f32_16x16x4_f32 v[36:39], v191, v13, v[36:39]
	s_nop 7
	s_nop 1
	s_waitcnt lgkmcnt(3)
	v_mfma_f32_16x16x4_f32 v[14:17], v192, v36, 0
	v_mfma_f32_16x16x4_f32 v[14:17], v193, v37, v[14:17]
	v_mfma_f32_16x16x4_f32 v[14:17], v194, v38, v[14:17]
	v_mfma_f32_16x16x4_f32 v[14:17], v195, v39, v[14:17]
	s_waitcnt lgkmcnt(2)
	v_mfma_f32_16x16x4_f32 v[240:243], v196, v10, 0
	v_mfma_f32_16x16x4_f32 v[240:243], v197, v11, v[240:243]
	v_mfma_f32_16x16x4_f32 v[240:243], v198, v12, v[240:243]
	v_mfma_f32_16x16x4_f32 v[240:243], v199, v13, v[240:243]
	s_nop 5
	s_waitcnt lgkmcnt(1)
	v_mfma_f32_16x16x4_f32 v[240:243], v200, v14, v[240:243]
	v_mfma_f32_16x16x4_f32 v[240:243], v201, v15, v[240:243]
	v_mfma_f32_16x16x4_f32 v[240:243], v202, v16, v[240:243]
	v_mfma_f32_16x16x4_f32 v[240:243], v203, v17, v[240:243]
	v_cvt_pk_bf16_f32 v9, v14, v14
	ds_write_b16 v8, v9 offset:4640
	v_cvt_pk_bf16_f32 v9, v15, v15
	ds_write_b16 v8, v9 offset:4784
	v_cvt_pk_bf16_f32 v9, v16, v16
	ds_write_b16 v8, v9 offset:4928
	v_cvt_pk_bf16_f32 v9, v17, v17
	ds_write_b16 v8, v9 offset:5072
	s_nop 1
	s_waitcnt lgkmcnt(4)
	v_mfma_f32_16x16x4_f32 v[164:167], v220, v240, 0
	v_mfma_f32_16x16x4_f32 v[164:167], v221, v241, v[164:167]
	v_mfma_f32_16x16x4_f32 v[164:167], v222, v242, v[164:167]
	v_mfma_f32_16x16x4_f32 v[164:167], v223, v243, v[164:167]
	s_nop 7
	s_nop 1
	v_cvt_pk_bf16_f32 v9, v164, v164
	ds_write_b16 v8, v9 offset:6944
	v_cvt_pk_bf16_f32 v9, v165, v165
	ds_write_b16 v8, v9 offset:7088
	v_cvt_pk_bf16_f32 v9, v166, v166
	ds_write_b16 v8, v9 offset:7232
	v_cvt_pk_bf16_f32 v9, v167, v167
	ds_write_b16 v8, v9 offset:7376
	s_branch .Llev_done
.Llev_col2:
	ds_read_b32 v10, v7 offset:2048
	ds_read_b32 v11, v7 offset:2112
	ds_read_b32 v12, v7 offset:2176
	ds_read_b32 v13, v7 offset:2240
	ds_read_b128 v[188:191], v4 offset:12416
	ds_read_b128 v[192:195], v5 offset:3072
	s_waitcnt lgkmcnt(1)
	v_mfma_f32_16x16x4_f32 v[36:39], v188, v10, 0
	v_mfma_f32_16x16x4_f32 v[36:39], v189, v11, v[36:39]
	v_mfma_f32_16x16x4_f32 v[36:39], v190, v12, v[36:39]
	v_mfma_f32_16x16x4_f32 v[36:39], v191, v13, v[36:39]
	s_nop 7
	s_nop 1
	s_waitcnt lgkmcnt(0)
	v_mfma_f32_16x16x4_f32 v[14:17], v192, v36, 0
	v_mfma_f32_16x16x4_f32 v[14:17], v193, v37, v[14:17]
	v_mfma_f32_16x16x4_f32 v[14:17], v194, v38, v[14:17]
	v_mfma_f32_16x16x4_f32 v[14:17], v195, v39, v[14:17]
	s_nop 7
	s_nop 1
	v_cvt_pk_bf16_f32 v9, v14, v14
	ds_write_b16 v8, v9 offset:6976
	v_cvt_pk_bf16_f32 v9, v15, v15
	ds_write_b16 v8, v9 offset:7120
	v_cvt_pk_bf16_f32 v9, v16, v16
	ds_write_b16 v8, v9 offset:7264
	v_cvt_pk_bf16_f32 v9, v17, v17
	ds_write_b16 v8, v9 offset:7408
